# merge epilogue last branch (denominator 255): specialised copy without the select/u8->f32/rcp of the constant denominator
# baseline (speedup 1.0000x reference)
.LBB0_583:
	s_mul_i32 s1, s13, 0x2c0000
	s_mul_hi_i32 s0, s13, 0x2c0000
	s_add_u32 s12, s19, s1
	s_addc_u32 s52, s25, s0
	s_ashr_i32 s57, s56, 31
	s_lshl_b64 s[0:1], s[56:57], 9
	v_mul_lo_u32 v26, v26, s7
	s_add_u32 s0, s12, s0
	v_or_b32_e32 v26, v26, v228
	s_addc_u32 s1, s52, s1
	s_waitcnt vmcnt(0)
	v_lshl_add_u64 v[220:221], s[0:1], 0, v[26:27]
	v_cndmask_b32_e64 v26, v218, -1, s[40:41]
	v_cvt_f32_ubyte0_e32 v152, v26
	v_rcp_iflag_f32_e32 v230, v152
	v_cvt_f32_ubyte1_e32 v152, v26
	v_rcp_iflag_f32_e32 v231, v152
	v_cvt_f32_ubyte1_e32 v233, v216
	v_cvt_f32_ubyte0_e32 v232, v216
	v_cvt_f32_ubyte2_e32 v218, v26
	v_cvt_f32_ubyte3_e32 v26, v26
	v_pk_mul_f32 v[230:231], v[230:231], v[232:233]
	v_rcp_iflag_f32_e32 v233, v26
	v_cndmask_b32_e64 v26, v219, -1, s[40:41]
	v_rcp_iflag_f32_e32 v232, v218
	v_pk_mul_f32 v[2:3], v[2:3], v[230:231]
	v_cvt_f32_ubyte3_e32 v231, v216
	v_cvt_f32_ubyte2_e32 v230, v216
	v_cvt_f32_ubyte0_e32 v216, v26
	v_rcp_iflag_f32_e32 v218, v216
	v_cvt_f32_ubyte1_e32 v216, v26
	v_rcp_iflag_f32_e32 v219, v216
	v_pk_mul_f32 v[230:231], v[232:233], v[230:231]
	v_cvt_f32_ubyte2_e32 v216, v26
	v_pk_mul_f32 v[4:5], v[4:5], v[230:231]
	v_cvt_f32_ubyte1_e32 v231, v217
	v_cvt_f32_ubyte0_e32 v230, v217
	v_cvt_f32_ubyte3_e32 v26, v26
	v_pk_mul_f32 v[218:219], v[218:219], v[230:231]
	v_rcp_iflag_f32_e32 v230, v216
	v_rcp_iflag_f32_e32 v231, v26
	v_pk_mul_f32 v[6:7], v[6:7], v[218:219]
	v_cvt_f32_ubyte3_e32 v219, v217
	v_cvt_f32_ubyte2_e32 v218, v217
	v_pk_mul_f32 v[216:217], v[230:231], v[218:219]
	v_cndmask_b32_e64 v26, 0, 1, s[40:41]
	v_lshl_add_u64 v[152:153], v[220:221], 0, s[86:87]
	v_cmp_ne_u32_e64 s[0:1], 1, v26
	s_andn2_b64 vcc, exec, s[40:41]
	v_pk_mul_f32 v[8:9], v[8:9], v[216:217]
	s_cbranch_vccnz .LBB0_585
	v_cvt_pk_bf16_f32 v216, v2, v3
	v_cvt_pk_bf16_f32 v217, v4, v5
	v_cvt_pk_bf16_f32 v218, v6, v7
	v_cvt_pk_bf16_f32 v219, v8, v9
	global_store_dwordx4 v[152:153], v[216:219], off
	s_branch .Lfin_585

.Lfin_585:
	v_mov_b32_e32 v248, 0x437f0000
	v_rcp_iflag_f32_e32 v248, v248
	s_nop 0
	v_mov_b32_e32 v249, v248
	v_cvt_f32_ubyte1_e32 v219, v212
	v_cvt_f32_ubyte0_e32 v218, v212
	v_pk_mul_f32 v[216:217], v[248:249], v[218:219]
	v_pk_mul_f32 v[36:37], v[36:37], v[216:217]
	v_cvt_f32_ubyte3_e32 v217, v212
	v_cvt_f32_ubyte2_e32 v216, v212
	v_pk_mul_f32 v[216:217], v[248:249], v[216:217]
	v_pk_mul_f32 v[38:39], v[38:39], v[216:217]
	v_cvt_f32_ubyte1_e32 v217, v213
	v_cvt_f32_ubyte0_e32 v216, v213
	v_pk_mul_f32 v[214:215], v[248:249], v[216:217]
	v_pk_mul_f32 v[40:41], v[40:41], v[214:215]
	v_cvt_f32_ubyte3_e32 v215, v213
	v_cvt_f32_ubyte2_e32 v214, v213
	v_pk_mul_f32 v[212:213], v[248:249], v[214:215]
	s_and_b64 vcc, exec, s[0:1]
	v_pk_mul_f32 v[42:43], v[42:43], v[212:213]
	v_cvt_pk_bf16_f32 v212, v36, v37
	v_cvt_pk_bf16_f32 v213, v38, v39
	v_cvt_pk_bf16_f32 v214, v40, v41
	v_cvt_pk_bf16_f32 v215, v42, v43
	global_store_dwordx4 v[220:221], v[212:215], off offset:3328
	s_nop 1
	v_cvt_f32_ubyte1_e32 v215, v208
	v_cvt_f32_ubyte0_e32 v214, v208
	v_pk_mul_f32 v[212:213], v[248:249], v[214:215]
	v_pk_mul_f32 v[10:11], v[10:11], v[212:213]
	v_cvt_f32_ubyte3_e32 v213, v208
	v_cvt_f32_ubyte2_e32 v212, v208
	v_pk_mul_f32 v[212:213], v[248:249], v[212:213]
	v_pk_mul_f32 v[12:13], v[12:13], v[212:213]
	v_cvt_f32_ubyte1_e32 v213, v209
	v_cvt_f32_ubyte0_e32 v212, v209
	v_pk_mul_f32 v[210:211], v[248:249], v[212:213]
	v_pk_mul_f32 v[14:15], v[14:15], v[210:211]
	v_cvt_f32_ubyte3_e32 v211, v209
	v_cvt_f32_ubyte2_e32 v210, v209
	v_pk_mul_f32 v[208:209], v[248:249], v[210:211]
	s_and_b64 vcc, exec, s[0:1]
	v_pk_mul_f32 v[16:17], v[16:17], v[208:209]
	v_add_co_u32_e32 v212, vcc, 0x2c000, v152
	v_cvt_pk_bf16_f32 v208, v10, v11
	v_cvt_pk_bf16_f32 v209, v12, v13
	v_cvt_pk_bf16_f32 v210, v14, v15
	v_cvt_pk_bf16_f32 v211, v16, v17
	s_nop 1
	v_addc_co_u32_e32 v213, vcc, 0, v153, vcc
	global_store_dwordx4 v[212:213], v[208:211], off
	s_nop 1
	v_cvt_f32_ubyte1_e32 v211, v204
	v_cvt_f32_ubyte0_e32 v210, v204
	v_pk_mul_f32 v[208:209], v[248:249], v[210:211]
	v_pk_mul_f32 v[44:45], v[44:45], v[208:209]
	v_cvt_f32_ubyte3_e32 v209, v204
	v_cvt_f32_ubyte2_e32 v208, v204
	v_pk_mul_f32 v[208:209], v[248:249], v[208:209]
	v_pk_mul_f32 v[46:47], v[46:47], v[208:209]
	v_cvt_f32_ubyte1_e32 v209, v205
	v_cvt_f32_ubyte0_e32 v208, v205
	v_pk_mul_f32 v[206:207], v[248:249], v[208:209]
	v_pk_mul_f32 v[48:49], v[48:49], v[206:207]
	v_cvt_f32_ubyte3_e32 v207, v205
	v_cvt_f32_ubyte2_e32 v206, v205
	v_pk_mul_f32 v[204:205], v[248:249], v[206:207]
	s_and_b64 vcc, exec, s[0:1]
	v_pk_mul_f32 v[50:51], v[50:51], v[204:205]
	v_add_co_u32_e32 v208, vcc, 0x2c000, v152
	v_cvt_pk_bf16_f32 v204, v44, v45
	v_cvt_pk_bf16_f32 v205, v46, v47
	v_cvt_pk_bf16_f32 v206, v48, v49
	v_cvt_pk_bf16_f32 v207, v50, v51
	s_nop 1
	v_addc_co_u32_e32 v209, vcc, 0, v153, vcc
	global_store_dwordx4 v[208:209], v[204:207], off offset:256
	s_nop 1
	v_cvt_f32_ubyte1_e32 v207, v200
	v_cvt_f32_ubyte0_e32 v206, v200
	v_pk_mul_f32 v[204:205], v[248:249], v[206:207]
	v_pk_mul_f32 v[18:19], v[18:19], v[204:205]
	v_cvt_f32_ubyte3_e32 v205, v200
	v_cvt_f32_ubyte2_e32 v204, v200
	v_pk_mul_f32 v[204:205], v[248:249], v[204:205]
	v_pk_mul_f32 v[20:21], v[20:21], v[204:205]
	v_cvt_f32_ubyte1_e32 v205, v201
	v_cvt_f32_ubyte0_e32 v204, v201
	v_pk_mul_f32 v[202:203], v[248:249], v[204:205]
	v_pk_mul_f32 v[22:23], v[22:23], v[202:203]
	v_cvt_f32_ubyte3_e32 v203, v201
	v_cvt_f32_ubyte2_e32 v202, v201
	v_pk_mul_f32 v[200:201], v[248:249], v[202:203]
	s_and_b64 vcc, exec, s[0:1]
	v_pk_mul_f32 v[24:25], v[24:25], v[200:201]
	v_add_co_u32_e32 v204, vcc, 0x58000, v152
	v_cvt_pk_bf16_f32 v200, v18, v19
	v_cvt_pk_bf16_f32 v201, v20, v21
	v_cvt_pk_bf16_f32 v202, v22, v23
	v_cvt_pk_bf16_f32 v203, v24, v25
	s_nop 1
	v_addc_co_u32_e32 v205, vcc, 0, v153, vcc
	global_store_dwordx4 v[204:205], v[200:203], off
	s_nop 1
	v_cvt_f32_ubyte1_e32 v203, v196
	v_cvt_f32_ubyte0_e32 v202, v196
	v_pk_mul_f32 v[200:201], v[248:249], v[202:203]
	v_pk_mul_f32 v[52:53], v[52:53], v[200:201]
	v_cvt_f32_ubyte3_e32 v201, v196
	v_cvt_f32_ubyte2_e32 v200, v196
	v_pk_mul_f32 v[200:201], v[248:249], v[200:201]
	v_pk_mul_f32 v[54:55], v[54:55], v[200:201]
	v_cvt_f32_ubyte1_e32 v201, v197
	v_cvt_f32_ubyte0_e32 v200, v197
	v_pk_mul_f32 v[198:199], v[248:249], v[200:201]
	v_pk_mul_f32 v[56:57], v[56:57], v[198:199]
	v_cvt_f32_ubyte3_e32 v199, v197
	v_cvt_f32_ubyte2_e32 v198, v197
	v_pk_mul_f32 v[196:197], v[248:249], v[198:199]
	s_and_b64 vcc, exec, s[0:1]
	v_pk_mul_f32 v[58:59], v[58:59], v[196:197]
	v_add_co_u32_e32 v200, vcc, 0x58000, v152
	v_cvt_pk_bf16_f32 v196, v52, v53
	v_cvt_pk_bf16_f32 v197, v54, v55
	v_cvt_pk_bf16_f32 v198, v56, v57
	v_cvt_pk_bf16_f32 v199, v58, v59
	s_nop 1
	v_addc_co_u32_e32 v201, vcc, 0, v153, vcc
	global_store_dwordx4 v[200:201], v[196:199], off offset:256
	s_nop 1
	v_cvt_f32_ubyte1_e32 v199, v192
	v_cvt_f32_ubyte0_e32 v198, v192
	v_pk_mul_f32 v[196:197], v[248:249], v[198:199]
	v_pk_mul_f32 v[28:29], v[28:29], v[196:197]
	v_cvt_f32_ubyte3_e32 v197, v192
	v_cvt_f32_ubyte2_e32 v196, v192
	v_pk_mul_f32 v[196:197], v[248:249], v[196:197]
	v_pk_mul_f32 v[30:31], v[30:31], v[196:197]
	v_cvt_f32_ubyte1_e32 v197, v193
	v_cvt_f32_ubyte0_e32 v196, v193
	v_pk_mul_f32 v[194:195], v[248:249], v[196:197]
	v_pk_mul_f32 v[32:33], v[32:33], v[194:195]
	v_cvt_f32_ubyte3_e32 v195, v193
	v_cvt_f32_ubyte2_e32 v194, v193
	v_pk_mul_f32 v[192:193], v[248:249], v[194:195]
	s_and_b64 vcc, exec, s[0:1]
	v_pk_mul_f32 v[34:35], v[34:35], v[192:193]
	v_add_co_u32_e32 v196, vcc, 0x84000, v152
	v_cvt_pk_bf16_f32 v192, v28, v29
	v_cvt_pk_bf16_f32 v193, v30, v31
	v_cvt_pk_bf16_f32 v194, v32, v33
	v_cvt_pk_bf16_f32 v195, v34, v35
	s_nop 1
	v_addc_co_u32_e32 v197, vcc, 0, v153, vcc
	global_store_dwordx4 v[196:197], v[192:195], off
	s_nop 1
	v_cvt_f32_ubyte1_e32 v195, v188
	v_cvt_f32_ubyte0_e32 v194, v188
	v_pk_mul_f32 v[192:193], v[248:249], v[194:195]
	v_pk_mul_f32 v[60:61], v[60:61], v[192:193]
	v_cvt_f32_ubyte3_e32 v193, v188
	v_cvt_f32_ubyte2_e32 v192, v188
	v_pk_mul_f32 v[192:193], v[248:249], v[192:193]
	v_pk_mul_f32 v[62:63], v[62:63], v[192:193]
	v_cvt_f32_ubyte1_e32 v193, v189
	v_cvt_f32_ubyte0_e32 v192, v189
	v_pk_mul_f32 v[190:191], v[248:249], v[192:193]
	v_pk_mul_f32 v[64:65], v[64:65], v[190:191]
	v_cvt_f32_ubyte3_e32 v191, v189
	v_cvt_f32_ubyte2_e32 v190, v189
	v_pk_mul_f32 v[188:189], v[248:249], v[190:191]
	s_and_b64 vcc, exec, s[0:1]
	v_pk_mul_f32 v[66:67], v[66:67], v[188:189]
	v_add_co_u32_e32 v192, vcc, 0x84000, v152
	v_cvt_pk_bf16_f32 v188, v60, v61
	v_cvt_pk_bf16_f32 v189, v62, v63
	v_cvt_pk_bf16_f32 v190, v64, v65
	v_cvt_pk_bf16_f32 v191, v66, v67
	s_nop 1
	v_addc_co_u32_e32 v193, vcc, 0, v153, vcc
	global_store_dwordx4 v[192:193], v[188:191], off offset:256
	s_nop 1
	v_cvt_f32_ubyte1_e32 v191, v184
	v_cvt_f32_ubyte0_e32 v190, v184
	v_pk_mul_f32 v[188:189], v[248:249], v[190:191]
	v_pk_mul_f32 v[68:69], v[68:69], v[188:189]
	v_cvt_f32_ubyte3_e32 v189, v184
	v_cvt_f32_ubyte2_e32 v188, v184
	v_pk_mul_f32 v[188:189], v[248:249], v[188:189]
	v_pk_mul_f32 v[70:71], v[70:71], v[188:189]
	v_cvt_f32_ubyte1_e32 v189, v185
	v_cvt_f32_ubyte0_e32 v188, v185
	v_pk_mul_f32 v[186:187], v[248:249], v[188:189]
	v_pk_mul_f32 v[72:73], v[72:73], v[186:187]
	v_cvt_f32_ubyte3_e32 v187, v185
	v_cvt_f32_ubyte2_e32 v186, v185
	v_pk_mul_f32 v[184:185], v[248:249], v[186:187]
	s_and_b64 vcc, exec, s[0:1]
	v_pk_mul_f32 v[74:75], v[74:75], v[184:185]
	v_add_co_u32_e32 v188, vcc, 0x160000, v152
	v_cvt_pk_bf16_f32 v184, v68, v69
	v_cvt_pk_bf16_f32 v185, v70, v71
	v_cvt_pk_bf16_f32 v186, v72, v73
	v_cvt_pk_bf16_f32 v187, v74, v75
	s_nop 1
	v_addc_co_u32_e32 v189, vcc, 0, v153, vcc
	global_store_dwordx4 v[188:189], v[184:187], off
	s_nop 1
	v_cvt_f32_ubyte1_e32 v187, v180
	v_cvt_f32_ubyte0_e32 v186, v180
	v_pk_mul_f32 v[184:185], v[248:249], v[186:187]
	v_pk_mul_f32 v[100:101], v[100:101], v[184:185]
	v_cvt_f32_ubyte3_e32 v185, v180
	v_cvt_f32_ubyte2_e32 v184, v180
	v_pk_mul_f32 v[184:185], v[248:249], v[184:185]
	v_pk_mul_f32 v[102:103], v[102:103], v[184:185]
	v_cvt_f32_ubyte1_e32 v185, v181
	v_cvt_f32_ubyte0_e32 v184, v181
	v_pk_mul_f32 v[182:183], v[248:249], v[184:185]
	v_pk_mul_f32 v[104:105], v[104:105], v[182:183]
	v_cvt_f32_ubyte3_e32 v183, v181
	v_cvt_f32_ubyte2_e32 v182, v181
	v_pk_mul_f32 v[180:181], v[248:249], v[182:183]
	s_and_b64 vcc, exec, s[0:1]
	v_pk_mul_f32 v[106:107], v[106:107], v[180:181]
	v_add_co_u32_e32 v184, vcc, 0x160000, v152
	v_cvt_pk_bf16_f32 v180, v100, v101
	v_cvt_pk_bf16_f32 v181, v102, v103
	v_cvt_pk_bf16_f32 v182, v104, v105
	v_cvt_pk_bf16_f32 v183, v106, v107
	s_nop 1
	v_addc_co_u32_e32 v185, vcc, 0, v153, vcc
	global_store_dwordx4 v[184:185], v[180:183], off offset:256
	s_nop 1
	v_cvt_f32_ubyte1_e32 v183, v176
	v_cvt_f32_ubyte0_e32 v182, v176
	v_pk_mul_f32 v[180:181], v[248:249], v[182:183]
	v_pk_mul_f32 v[76:77], v[76:77], v[180:181]
	v_cvt_f32_ubyte3_e32 v181, v176
	v_cvt_f32_ubyte2_e32 v180, v176
	v_pk_mul_f32 v[180:181], v[248:249], v[180:181]
	v_pk_mul_f32 v[78:79], v[78:79], v[180:181]
	v_cvt_f32_ubyte1_e32 v181, v177
	v_cvt_f32_ubyte0_e32 v180, v177
	v_pk_mul_f32 v[178:179], v[248:249], v[180:181]
	v_pk_mul_f32 v[80:81], v[80:81], v[178:179]
	v_cvt_f32_ubyte3_e32 v179, v177
	v_cvt_f32_ubyte2_e32 v178, v177
	v_pk_mul_f32 v[176:177], v[248:249], v[178:179]
	s_and_b64 vcc, exec, s[0:1]
	v_pk_mul_f32 v[82:83], v[82:83], v[176:177]
	v_add_co_u32_e32 v180, vcc, 0x18c000, v152
	v_cvt_pk_bf16_f32 v176, v76, v77
	v_cvt_pk_bf16_f32 v177, v78, v79
	v_cvt_pk_bf16_f32 v178, v80, v81
	v_cvt_pk_bf16_f32 v179, v82, v83
	s_nop 1
	v_addc_co_u32_e32 v181, vcc, 0, v153, vcc
	global_store_dwordx4 v[180:181], v[176:179], off
	s_nop 1
	v_cvt_f32_ubyte1_e32 v179, v164
	v_cvt_f32_ubyte0_e32 v178, v164
	v_pk_mul_f32 v[176:177], v[248:249], v[178:179]
	v_pk_mul_f32 v[108:109], v[108:109], v[176:177]
	v_cvt_f32_ubyte3_e32 v177, v164
	v_cvt_f32_ubyte2_e32 v176, v164
	v_pk_mul_f32 v[176:177], v[248:249], v[176:177]
	v_pk_mul_f32 v[110:111], v[110:111], v[176:177]
	v_cvt_f32_ubyte1_e32 v177, v165
	v_cvt_f32_ubyte0_e32 v176, v165
	v_pk_mul_f32 v[166:167], v[248:249], v[176:177]
	v_pk_mul_f32 v[112:113], v[112:113], v[166:167]
	v_cvt_f32_ubyte3_e32 v167, v165
	v_cvt_f32_ubyte2_e32 v166, v165
	v_pk_mul_f32 v[164:165], v[248:249], v[166:167]
	s_and_b64 vcc, exec, s[0:1]
	v_pk_mul_f32 v[114:115], v[114:115], v[164:165]
	v_add_co_u32_e32 v176, vcc, 0x18c000, v152
	v_cvt_pk_bf16_f32 v164, v108, v109
	v_cvt_pk_bf16_f32 v165, v110, v111
	v_cvt_pk_bf16_f32 v166, v112, v113
	v_cvt_pk_bf16_f32 v167, v114, v115
	s_nop 1
	v_addc_co_u32_e32 v177, vcc, 0, v153, vcc
	global_store_dwordx4 v[176:177], v[164:167], off offset:256
	s_nop 1
	v_cvt_f32_ubyte1_e32 v167, v160
	v_cvt_f32_ubyte0_e32 v166, v160
	v_pk_mul_f32 v[164:165], v[248:249], v[166:167]
	v_pk_mul_f32 v[84:85], v[84:85], v[164:165]
	v_cvt_f32_ubyte3_e32 v165, v160
	v_cvt_f32_ubyte2_e32 v164, v160
	v_pk_mul_f32 v[164:165], v[248:249], v[164:165]
	v_pk_mul_f32 v[86:87], v[86:87], v[164:165]
	v_cvt_f32_ubyte1_e32 v165, v161
	v_cvt_f32_ubyte0_e32 v164, v161
	v_pk_mul_f32 v[162:163], v[248:249], v[164:165]
	v_pk_mul_f32 v[88:89], v[88:89], v[162:163]
	v_cvt_f32_ubyte3_e32 v163, v161
	v_cvt_f32_ubyte2_e32 v162, v161
	v_pk_mul_f32 v[160:161], v[248:249], v[162:163]
	s_and_b64 vcc, exec, s[0:1]
	v_pk_mul_f32 v[90:91], v[90:91], v[160:161]
	v_add_co_u32_e32 v164, vcc, 0x1b8000, v152
	v_cvt_pk_bf16_f32 v160, v84, v85
	v_cvt_pk_bf16_f32 v161, v86, v87
	v_cvt_pk_bf16_f32 v162, v88, v89
	v_cvt_pk_bf16_f32 v163, v90, v91
	s_nop 1
	v_addc_co_u32_e32 v165, vcc, 0, v153, vcc
	global_store_dwordx4 v[164:165], v[160:163], off
	s_nop 1
	v_cvt_f32_ubyte1_e32 v163, v156
	v_cvt_f32_ubyte0_e32 v162, v156
	v_pk_mul_f32 v[160:161], v[248:249], v[162:163]
	v_pk_mul_f32 v[116:117], v[116:117], v[160:161]
	v_cvt_f32_ubyte3_e32 v161, v156
	v_cvt_f32_ubyte2_e32 v160, v156
	v_pk_mul_f32 v[160:161], v[248:249], v[160:161]
	v_pk_mul_f32 v[118:119], v[118:119], v[160:161]
	v_cvt_f32_ubyte1_e32 v161, v157
	v_cvt_f32_ubyte0_e32 v160, v157
	v_pk_mul_f32 v[158:159], v[248:249], v[160:161]
	v_pk_mul_f32 v[120:121], v[120:121], v[158:159]
	v_cvt_f32_ubyte3_e32 v159, v157
	v_cvt_f32_ubyte2_e32 v158, v157
	v_pk_mul_f32 v[156:157], v[248:249], v[158:159]
	s_and_b64 vcc, exec, s[0:1]
	v_pk_mul_f32 v[122:123], v[122:123], v[156:157]
	v_add_co_u32_e32 v160, vcc, 0x1b8000, v152
	v_cvt_pk_bf16_f32 v156, v116, v117
	v_cvt_pk_bf16_f32 v157, v118, v119
	v_cvt_pk_bf16_f32 v158, v120, v121
	v_cvt_pk_bf16_f32 v159, v122, v123
	s_nop 1
	v_addc_co_u32_e32 v161, vcc, 0, v153, vcc
	global_store_dwordx4 v[160:161], v[156:159], off offset:256
	s_nop 1
	v_cvt_f32_ubyte1_e32 v159, v150
	v_cvt_f32_ubyte0_e32 v158, v150
	v_pk_mul_f32 v[156:157], v[248:249], v[158:159]
	v_pk_mul_f32 v[92:93], v[92:93], v[156:157]
	v_cvt_f32_ubyte3_e32 v157, v150
	v_cvt_f32_ubyte2_e32 v156, v150
	v_pk_mul_f32 v[156:157], v[248:249], v[156:157]
	v_pk_mul_f32 v[94:95], v[94:95], v[156:157]
	v_cvt_f32_ubyte1_e32 v157, v151
	v_cvt_f32_ubyte0_e32 v156, v151
	v_pk_mul_f32 v[154:155], v[248:249], v[156:157]
	v_pk_mul_f32 v[96:97], v[96:97], v[154:155]
	v_cvt_f32_ubyte3_e32 v155, v151
	v_cvt_f32_ubyte2_e32 v154, v151
	v_pk_mul_f32 v[150:151], v[248:249], v[154:155]
	s_and_b64 vcc, exec, s[0:1]
	v_pk_mul_f32 v[98:99], v[98:99], v[150:151]
	v_add_co_u32_e32 v150, vcc, 0x1e4000, v152
	v_cvt_pk_bf16_f32 v154, v92, v93
	v_cvt_pk_bf16_f32 v155, v94, v95
	v_cvt_pk_bf16_f32 v156, v96, v97
	v_cvt_pk_bf16_f32 v157, v98, v99
	s_nop 1
	v_addc_co_u32_e32 v151, vcc, 0, v153, vcc
	global_store_dwordx4 v[150:151], v[154:157], off
	s_nop 1
	v_cvt_f32_ubyte1_e32 v155, v146
	v_cvt_f32_ubyte0_e32 v154, v146
	v_pk_mul_f32 v[150:151], v[248:249], v[154:155]
	v_pk_mul_f32 v[124:125], v[124:125], v[150:151]
	v_cvt_f32_ubyte3_e32 v151, v146
	v_cvt_f32_ubyte2_e32 v150, v146
	v_pk_mul_f32 v[150:151], v[248:249], v[150:151]
	v_pk_mul_f32 v[126:127], v[126:127], v[150:151]
	v_cvt_f32_ubyte1_e32 v151, v147
	v_cvt_f32_ubyte0_e32 v150, v147
	v_pk_mul_f32 v[148:149], v[248:249], v[150:151]
	v_pk_mul_f32 v[128:129], v[128:129], v[148:149]
	v_cvt_f32_ubyte3_e32 v149, v147
	v_cvt_f32_ubyte2_e32 v148, v147
	v_pk_mul_f32 v[146:147], v[248:249], v[148:149]
	s_and_b64 vcc, exec, s[0:1]
	v_pk_mul_f32 v[130:131], v[130:131], v[146:147]
	v_add_co_u32_e32 v150, vcc, 0x1e4000, v152
	v_cvt_pk_bf16_f32 v146, v124, v125
	v_cvt_pk_bf16_f32 v147, v126, v127
	v_cvt_pk_bf16_f32 v148, v128, v129
	v_cvt_pk_bf16_f32 v149, v130, v131
	s_nop 1
	v_addc_co_u32_e32 v151, vcc, 0, v153, vcc
	global_store_dwordx4 v[150:151], v[146:149], off offset:256
	s_nop 1
	s_branch .LBB0_615
